# WC-table generation loop batched (8 iterations of gather loads in flight) on top of v20
# baseline (speedup 1.0000x reference)
; __device__ __forceinline__ unsigned pk2(float lo, float hi) { return pg8::cvt_pk_bf16(lo, hi); }
; __device__ __forceinline__ void ssm_tables(unsigned char* ws, int l, const int tid) {
;     ...
;     for (int it = gt; it < NG * LCH * NP * 2 * NS; it += NGT) { const int n = it & 63, dir = (it >> 6) & 1, p = (it >> 7) & 15, i = (it >> 11) & 63, g = it >> 17;
;         const f32x2 pw = ptab[(size_t)((g * 2 + dir) * NS + n) * 65 + (dir ? 64 - i : i + 1)];
;         const float cr = cre[(g * NP + p) * NS + n], ci = cim[(g * NP + p) * NS + n];
;         ((unsigned*)WC)[((size_t)(g * 1024 + i * 16 + p) * 256 + dir * 128 + 2 * n) >> 1] = pk2(cr * pw.x - ci * pw.y, -(cr * pw.y + ci * pw.x)); }
.LBB0_271:
	s_or_b64 exec, exec, s[34:35]
	s_mov_b32 s3, 0x400000
	v_cmp_gt_i32_e32 vcc, s3, v6
	s_and_saveexec_b64 s[34:35], vcc
	v_readlane_b32 s6, v252, 22
	v_readlane_b32 s7, v252, 23
	s_cbranch_execz .LBB0_274
	v_readlane_b32 s8, v252, 24
	v_readlane_b32 s9, v252, 25
	s_lshl_b64 s[14:15], s[8:9], 17
	v_readlane_b32 s36, v252, 18
	v_readlane_b32 s37, v252, 19
	s_add_u32 s36, s36, s14
	s_addc_u32 s37, s37, s15
	v_readlane_b32 s3, v251, 30
	s_add_u32 s38, s3, s14
	v_readlane_b32 s3, v251, 31
	s_addc_u32 s39, s3, s15
	v_lshlrev_b32_e32 v0, 1, v7
	s_mov_b64 s[40:41], 0
	s_cmp_eq_u32 s6, 0x20000
	s_cbranch_scc0 .LBB0_273
	s_waitcnt vmcnt(0)
	s_mov_b32 s3, 0
.Lwctab_batch:
	v_bfe_u32 v1, v6, 6, 1
	v_ashrrev_i32_e32 v2, 17, v6
	v_bfe_u32 v12, v6, 7, 4
	v_bfe_u32 v13, v6, 11, 6
	v_lshlrev_b32_e32 v3, 7, v2
	v_lshlrev_b32_e32 v8, 6, v1
	v_sub_u32_e32 v9, 64, v13
	v_add_u32_e32 v10, 1, v13
	v_cmp_eq_u32_e32 vcc, 0, v1
	v_lshlrev_b32_e32 v14, 10, v2
	v_lshlrev_b32_e32 v2, 6, v12
	v_or3_b32 v3, v8, v3, v7
	v_cndmask_b32_e32 v9, v9, v10, vcc
	v_or3_b32 v2, v2, v14, v7
	v_mul_i32_i24_e32 v8, 0x41, v3
	v_lshlrev_b32_e32 v184, 3, v9
	v_ashrrev_i32_e32 v3, 31, v2
	v_ashrrev_i32_e32 v9, 31, v8
	v_lshlrev_b64 v[2:3], 2, v[2:3]
	v_lshl_add_u64 v[8:9], v[8:9], 3, s[42:43]
	v_lshl_add_u64 v[10:11], s[36:37], 0, v[2:3]
	v_lshl_add_u64 v[8:9], v[8:9], 0, v[184:185]
	v_lshl_add_u64 v[2:3], s[38:39], 0, v[2:3]
	global_load_dwordx2 v[100:101], v[8:9], off
	global_load_dword v102, v[10:11], off
	global_load_dword v103, v[2:3], off
	v_lshlrev_b32_e32 v2, 4, v13
	v_or3_b32 v2, v2, v14, v12
	v_ashrrev_i32_e32 v3, 31, v2
	v_lshlrev_b64 v[2:3], 8, v[2:3]
	v_add_u32_e32 v6, s6, v6
	v_lshl_or_b32 v1, v1, 7, v2
	v_or_b32_e32 v2, v1, v0
	v_lshl_add_u64 v[104:105], v[2:3], 1, s[50:51]
	v_bfe_u32 v1, v6, 6, 1
	v_ashrrev_i32_e32 v2, 17, v6
	v_bfe_u32 v12, v6, 7, 4
	v_bfe_u32 v13, v6, 11, 6
	v_lshlrev_b32_e32 v3, 7, v2
	v_lshlrev_b32_e32 v8, 6, v1
	v_sub_u32_e32 v9, 64, v13
	v_add_u32_e32 v10, 1, v13
	v_cmp_eq_u32_e32 vcc, 0, v1
	v_lshlrev_b32_e32 v14, 10, v2
	v_lshlrev_b32_e32 v2, 6, v12
	v_or3_b32 v3, v8, v3, v7
	v_cndmask_b32_e32 v9, v9, v10, vcc
	v_or3_b32 v2, v2, v14, v7
	v_mul_i32_i24_e32 v8, 0x41, v3
	v_lshlrev_b32_e32 v184, 3, v9
	v_ashrrev_i32_e32 v3, 31, v2
	v_ashrrev_i32_e32 v9, 31, v8
	v_lshlrev_b64 v[2:3], 2, v[2:3]
	v_lshl_add_u64 v[8:9], v[8:9], 3, s[42:43]
	v_lshl_add_u64 v[10:11], s[36:37], 0, v[2:3]
	v_lshl_add_u64 v[8:9], v[8:9], 0, v[184:185]
	v_lshl_add_u64 v[2:3], s[38:39], 0, v[2:3]
	global_load_dwordx2 v[108:109], v[8:9], off
	global_load_dword v110, v[10:11], off
	global_load_dword v111, v[2:3], off
	v_lshlrev_b32_e32 v2, 4, v13
	v_or3_b32 v2, v2, v14, v12
	v_ashrrev_i32_e32 v3, 31, v2
	v_lshlrev_b64 v[2:3], 8, v[2:3]
	v_add_u32_e32 v6, s6, v6
	v_lshl_or_b32 v1, v1, 7, v2
	v_or_b32_e32 v2, v1, v0
	v_lshl_add_u64 v[112:113], v[2:3], 1, s[50:51]
	v_bfe_u32 v1, v6, 6, 1
	v_ashrrev_i32_e32 v2, 17, v6
	v_bfe_u32 v12, v6, 7, 4
	v_bfe_u32 v13, v6, 11, 6
	v_lshlrev_b32_e32 v3, 7, v2
	v_lshlrev_b32_e32 v8, 6, v1
	v_sub_u32_e32 v9, 64, v13
	v_add_u32_e32 v10, 1, v13
	v_cmp_eq_u32_e32 vcc, 0, v1
	v_lshlrev_b32_e32 v14, 10, v2
	v_lshlrev_b32_e32 v2, 6, v12
	v_or3_b32 v3, v8, v3, v7
	v_cndmask_b32_e32 v9, v9, v10, vcc
	v_or3_b32 v2, v2, v14, v7
	v_mul_i32_i24_e32 v8, 0x41, v3
	v_lshlrev_b32_e32 v184, 3, v9
	v_ashrrev_i32_e32 v3, 31, v2
	v_ashrrev_i32_e32 v9, 31, v8
	v_lshlrev_b64 v[2:3], 2, v[2:3]
	v_lshl_add_u64 v[8:9], v[8:9], 3, s[42:43]
	v_lshl_add_u64 v[10:11], s[36:37], 0, v[2:3]
	v_lshl_add_u64 v[8:9], v[8:9], 0, v[184:185]
	v_lshl_add_u64 v[2:3], s[38:39], 0, v[2:3]
	global_load_dwordx2 v[116:117], v[8:9], off
	global_load_dword v118, v[10:11], off
	global_load_dword v119, v[2:3], off
	v_lshlrev_b32_e32 v2, 4, v13
	v_or3_b32 v2, v2, v14, v12
	v_ashrrev_i32_e32 v3, 31, v2
	v_lshlrev_b64 v[2:3], 8, v[2:3]
	v_add_u32_e32 v6, s6, v6
	v_lshl_or_b32 v1, v1, 7, v2
	v_or_b32_e32 v2, v1, v0
	v_lshl_add_u64 v[120:121], v[2:3], 1, s[50:51]
	v_bfe_u32 v1, v6, 6, 1
	v_ashrrev_i32_e32 v2, 17, v6
	v_bfe_u32 v12, v6, 7, 4
	v_bfe_u32 v13, v6, 11, 6
	v_lshlrev_b32_e32 v3, 7, v2
	v_lshlrev_b32_e32 v8, 6, v1
	v_sub_u32_e32 v9, 64, v13
	v_add_u32_e32 v10, 1, v13
	v_cmp_eq_u32_e32 vcc, 0, v1
	v_lshlrev_b32_e32 v14, 10, v2
	v_lshlrev_b32_e32 v2, 6, v12
	v_or3_b32 v3, v8, v3, v7
	v_cndmask_b32_e32 v9, v9, v10, vcc
	v_or3_b32 v2, v2, v14, v7
	v_mul_i32_i24_e32 v8, 0x41, v3
	v_lshlrev_b32_e32 v184, 3, v9
	v_ashrrev_i32_e32 v3, 31, v2
	v_ashrrev_i32_e32 v9, 31, v8
	v_lshlrev_b64 v[2:3], 2, v[2:3]
	v_lshl_add_u64 v[8:9], v[8:9], 3, s[42:43]
	v_lshl_add_u64 v[10:11], s[36:37], 0, v[2:3]
	v_lshl_add_u64 v[8:9], v[8:9], 0, v[184:185]
	v_lshl_add_u64 v[2:3], s[38:39], 0, v[2:3]
	global_load_dwordx2 v[124:125], v[8:9], off
	global_load_dword v126, v[10:11], off
	global_load_dword v127, v[2:3], off
	v_lshlrev_b32_e32 v2, 4, v13
	v_or3_b32 v2, v2, v14, v12
	v_ashrrev_i32_e32 v3, 31, v2
	v_lshlrev_b64 v[2:3], 8, v[2:3]
	v_add_u32_e32 v6, s6, v6
	v_lshl_or_b32 v1, v1, 7, v2
	v_or_b32_e32 v2, v1, v0
	v_lshl_add_u64 v[128:129], v[2:3], 1, s[50:51]
	v_bfe_u32 v1, v6, 6, 1
	v_ashrrev_i32_e32 v2, 17, v6
	v_bfe_u32 v12, v6, 7, 4
	v_bfe_u32 v13, v6, 11, 6
	v_lshlrev_b32_e32 v3, 7, v2
	v_lshlrev_b32_e32 v8, 6, v1
	v_sub_u32_e32 v9, 64, v13
	v_add_u32_e32 v10, 1, v13
	v_cmp_eq_u32_e32 vcc, 0, v1
	v_lshlrev_b32_e32 v14, 10, v2
	v_lshlrev_b32_e32 v2, 6, v12
	v_or3_b32 v3, v8, v3, v7
	v_cndmask_b32_e32 v9, v9, v10, vcc
	v_or3_b32 v2, v2, v14, v7
	v_mul_i32_i24_e32 v8, 0x41, v3
	v_lshlrev_b32_e32 v184, 3, v9
	v_ashrrev_i32_e32 v3, 31, v2
	v_ashrrev_i32_e32 v9, 31, v8
	v_lshlrev_b64 v[2:3], 2, v[2:3]
; __device__ __forceinline__ unsigned pk2(float lo, float hi) { return pg8::cvt_pk_bf16(lo, hi); }
; __device__ __forceinline__ void ssm_tables(unsigned char* ws, int l, const int tid) {
;     ...
;     for (int it = gt; it < NG * LCH * NP * 2 * NS; it += NGT) { const int n = it & 63, dir = (it >> 6) & 1, p = (it >> 7) & 15, i = (it >> 11) & 63, g = it >> 17;
;         const f32x2 pw = ptab[(size_t)((g * 2 + dir) * NS + n) * 65 + (dir ? 64 - i : i + 1)];
;         const float cr = cre[(g * NP + p) * NS + n], ci = cim[(g * NP + p) * NS + n];
;         ((unsigned*)WC)[((size_t)(g * 1024 + i * 16 + p) * 256 + dir * 128 + 2 * n) >> 1] = pk2(cr * pw.x - ci * pw.y, -(cr * pw.y + ci * pw.x)); }
	v_lshl_add_u64 v[8:9], v[8:9], 3, s[42:43]
	v_lshl_add_u64 v[10:11], s[36:37], 0, v[2:3]
	v_lshl_add_u64 v[8:9], v[8:9], 0, v[184:185]
	v_lshl_add_u64 v[2:3], s[38:39], 0, v[2:3]
	global_load_dwordx2 v[132:133], v[8:9], off
	global_load_dword v134, v[10:11], off
	global_load_dword v135, v[2:3], off
	v_lshlrev_b32_e32 v2, 4, v13
	v_or3_b32 v2, v2, v14, v12
	v_ashrrev_i32_e32 v3, 31, v2
	v_lshlrev_b64 v[2:3], 8, v[2:3]
	v_add_u32_e32 v6, s6, v6
	v_lshl_or_b32 v1, v1, 7, v2
	v_or_b32_e32 v2, v1, v0
	v_lshl_add_u64 v[136:137], v[2:3], 1, s[50:51]
	v_bfe_u32 v1, v6, 6, 1
	v_ashrrev_i32_e32 v2, 17, v6
	v_bfe_u32 v12, v6, 7, 4
	v_bfe_u32 v13, v6, 11, 6
	v_lshlrev_b32_e32 v3, 7, v2
	v_lshlrev_b32_e32 v8, 6, v1
	v_sub_u32_e32 v9, 64, v13
	v_add_u32_e32 v10, 1, v13
	v_cmp_eq_u32_e32 vcc, 0, v1
	v_lshlrev_b32_e32 v14, 10, v2
	v_lshlrev_b32_e32 v2, 6, v12
	v_or3_b32 v3, v8, v3, v7
	v_cndmask_b32_e32 v9, v9, v10, vcc
	v_or3_b32 v2, v2, v14, v7
	v_mul_i32_i24_e32 v8, 0x41, v3
	v_lshlrev_b32_e32 v184, 3, v9
	v_ashrrev_i32_e32 v3, 31, v2
	v_ashrrev_i32_e32 v9, 31, v8
	v_lshlrev_b64 v[2:3], 2, v[2:3]
	v_lshl_add_u64 v[8:9], v[8:9], 3, s[42:43]
	v_lshl_add_u64 v[10:11], s[36:37], 0, v[2:3]
	v_lshl_add_u64 v[8:9], v[8:9], 0, v[184:185]
	v_lshl_add_u64 v[2:3], s[38:39], 0, v[2:3]
	global_load_dwordx2 v[144:145], v[8:9], off
	global_load_dword v146, v[10:11], off
	global_load_dword v147, v[2:3], off
	v_lshlrev_b32_e32 v2, 4, v13
	v_or3_b32 v2, v2, v14, v12
	v_ashrrev_i32_e32 v3, 31, v2
	v_lshlrev_b64 v[2:3], 8, v[2:3]
	v_add_u32_e32 v6, s6, v6
	v_lshl_or_b32 v1, v1, 7, v2
	v_or_b32_e32 v2, v1, v0
	v_lshl_add_u64 v[148:149], v[2:3], 1, s[50:51]
	v_bfe_u32 v1, v6, 6, 1
	v_ashrrev_i32_e32 v2, 17, v6
	v_bfe_u32 v12, v6, 7, 4
	v_bfe_u32 v13, v6, 11, 6
	v_lshlrev_b32_e32 v3, 7, v2
	v_lshlrev_b32_e32 v8, 6, v1
	v_sub_u32_e32 v9, 64, v13
	v_add_u32_e32 v10, 1, v13
	v_cmp_eq_u32_e32 vcc, 0, v1
	v_lshlrev_b32_e32 v14, 10, v2
	v_lshlrev_b32_e32 v2, 6, v12
	v_or3_b32 v3, v8, v3, v7
	v_cndmask_b32_e32 v9, v9, v10, vcc
	v_or3_b32 v2, v2, v14, v7
	v_mul_i32_i24_e32 v8, 0x41, v3
	v_lshlrev_b32_e32 v184, 3, v9
	v_ashrrev_i32_e32 v3, 31, v2
	v_ashrrev_i32_e32 v9, 31, v8
	v_lshlrev_b64 v[2:3], 2, v[2:3]
	v_lshl_add_u64 v[8:9], v[8:9], 3, s[42:43]
	v_lshl_add_u64 v[10:11], s[36:37], 0, v[2:3]
	v_lshl_add_u64 v[8:9], v[8:9], 0, v[184:185]
	v_lshl_add_u64 v[2:3], s[38:39], 0, v[2:3]
	global_load_dwordx2 v[152:153], v[8:9], off
	global_load_dword v154, v[10:11], off
	global_load_dword v155, v[2:3], off
	v_lshlrev_b32_e32 v2, 4, v13
	v_or3_b32 v2, v2, v14, v12
	v_ashrrev_i32_e32 v3, 31, v2
	v_lshlrev_b64 v[2:3], 8, v[2:3]
	v_add_u32_e32 v6, s6, v6
	v_lshl_or_b32 v1, v1, 7, v2
	v_or_b32_e32 v2, v1, v0
	v_lshl_add_u64 v[156:157], v[2:3], 1, s[50:51]
	v_bfe_u32 v1, v6, 6, 1
	v_ashrrev_i32_e32 v2, 17, v6
	v_bfe_u32 v12, v6, 7, 4
	v_bfe_u32 v13, v6, 11, 6
	v_lshlrev_b32_e32 v3, 7, v2
	v_lshlrev_b32_e32 v8, 6, v1
	v_sub_u32_e32 v9, 64, v13
	v_add_u32_e32 v10, 1, v13
	v_cmp_eq_u32_e32 vcc, 0, v1
	v_lshlrev_b32_e32 v14, 10, v2
	v_lshlrev_b32_e32 v2, 6, v12
	v_or3_b32 v3, v8, v3, v7
	v_cndmask_b32_e32 v9, v9, v10, vcc
	v_or3_b32 v2, v2, v14, v7
	v_mul_i32_i24_e32 v8, 0x41, v3
	v_lshlrev_b32_e32 v184, 3, v9
	v_ashrrev_i32_e32 v3, 31, v2
	v_ashrrev_i32_e32 v9, 31, v8
	v_lshlrev_b64 v[2:3], 2, v[2:3]
	v_lshl_add_u64 v[8:9], v[8:9], 3, s[42:43]
	v_lshl_add_u64 v[10:11], s[36:37], 0, v[2:3]
	v_lshl_add_u64 v[8:9], v[8:9], 0, v[184:185]
	v_lshl_add_u64 v[2:3], s[38:39], 0, v[2:3]
	global_load_dwordx2 v[160:161], v[8:9], off
	global_load_dword v162, v[10:11], off
	global_load_dword v163, v[2:3], off
	v_lshlrev_b32_e32 v2, 4, v13
	v_or3_b32 v2, v2, v14, v12
	v_ashrrev_i32_e32 v3, 31, v2
	v_lshlrev_b64 v[2:3], 8, v[2:3]
	v_add_u32_e32 v6, s6, v6
	v_lshl_or_b32 v1, v1, 7, v2
	v_or_b32_e32 v2, v1, v0
	v_lshl_add_u64 v[164:165], v[2:3], 1, s[50:51]
	s_waitcnt vmcnt(0)
	v_mov_b32_e32 v15, v102
	v_mov_b32_e32 v14, v103
	v_pk_mul_f32 v[12:13], v[102:103], v[100:101]
	v_pk_mul_f32 v[8:9], v[14:15], v[100:101]
	v_sub_f32_e32 v1, v12, v13
	v_add_f32_e32 v8, v9, v8
	v_xor_b32_e32 v8, 0x80000000, v8
	v_cvt_pk_bf16_f32 v1, v1, v8
	global_store_dword v[104:105], v1, off
	v_mov_b32_e32 v15, v110
	v_mov_b32_e32 v14, v111
	v_pk_mul_f32 v[12:13], v[110:111], v[108:109]
	v_pk_mul_f32 v[8:9], v[14:15], v[108:109]
	v_sub_f32_e32 v1, v12, v13
	v_add_f32_e32 v8, v9, v8
	v_xor_b32_e32 v8, 0x80000000, v8
	v_cvt_pk_bf16_f32 v1, v1, v8
	global_store_dword v[112:113], v1, off
	v_mov_b32_e32 v15, v118
	v_mov_b32_e32 v14, v119
	v_pk_mul_f32 v[12:13], v[118:119], v[116:117]
	v_pk_mul_f32 v[8:9], v[14:15], v[116:117]
	v_sub_f32_e32 v1, v12, v13
	v_add_f32_e32 v8, v9, v8
	v_xor_b32_e32 v8, 0x80000000, v8
	v_cvt_pk_bf16_f32 v1, v1, v8
	global_store_dword v[120:121], v1, off
	v_mov_b32_e32 v15, v126
	v_mov_b32_e32 v14, v127
	v_pk_mul_f32 v[12:13], v[126:127], v[124:125]
	v_pk_mul_f32 v[8:9], v[14:15], v[124:125]
	v_sub_f32_e32 v1, v12, v13
	v_add_f32_e32 v8, v9, v8
	v_xor_b32_e32 v8, 0x80000000, v8
	v_cvt_pk_bf16_f32 v1, v1, v8
	global_store_dword v[128:129], v1, off
	v_mov_b32_e32 v15, v134
	v_mov_b32_e32 v14, v135
	v_pk_mul_f32 v[12:13], v[134:135], v[132:133]
	v_pk_mul_f32 v[8:9], v[14:15], v[132:133]
	v_sub_f32_e32 v1, v12, v13
	v_add_f32_e32 v8, v9, v8
	v_xor_b32_e32 v8, 0x80000000, v8
	v_cvt_pk_bf16_f32 v1, v1, v8
	global_store_dword v[136:137], v1, off
	v_mov_b32_e32 v15, v146
	v_mov_b32_e32 v14, v147
	v_pk_mul_f32 v[12:13], v[146:147], v[144:145]
	v_pk_mul_f32 v[8:9], v[14:15], v[144:145]
	v_sub_f32_e32 v1, v12, v13
	v_add_f32_e32 v8, v9, v8
	v_xor_b32_e32 v8, 0x80000000, v8
	v_cvt_pk_bf16_f32 v1, v1, v8
	global_store_dword v[148:149], v1, off
	v_mov_b32_e32 v15, v154
	v_mov_b32_e32 v14, v155
	v_pk_mul_f32 v[12:13], v[154:155], v[152:153]
	v_pk_mul_f32 v[8:9], v[14:15], v[152:153]
	v_sub_f32_e32 v1, v12, v13
	v_add_f32_e32 v8, v9, v8
	v_xor_b32_e32 v8, 0x80000000, v8
	v_cvt_pk_bf16_f32 v1, v1, v8
	global_store_dword v[156:157], v1, off
	v_mov_b32_e32 v15, v162
	v_mov_b32_e32 v14, v163
	v_pk_mul_f32 v[12:13], v[162:163], v[160:161]
	v_pk_mul_f32 v[8:9], v[14:15], v[160:161]
	v_sub_f32_e32 v1, v12, v13
	v_add_f32_e32 v8, v9, v8
	v_xor_b32_e32 v8, 0x80000000, v8
	v_cvt_pk_bf16_f32 v1, v1, v8
	global_store_dword v[164:165], v1, off
	s_add_i32 s3, s3, 1
	s_cmp_lt_u32 s3, 4
	s_cbranch_scc1 .Lwctab_batch
	s_mov_b64 s[40:41], exec
	s_branch .LBB0_274
